# layer-0 short conv deferred: workgroups without a 16-row attention unit run the conv pass after their attention items (overlapping the other workgroups' leftover units) instead of all workgroups runni
# speedup vs baseline: 1.0054x; 1.0054x over previous
; __device__ __forceinline__ void conv_pass(const bf16* GB, const bf16* U, const float* cw  , bf16* AO, int gw, int NGW, int lane) {
;     const int c0 = lane * 8;
;     f32x4 w[3][2];
; #pragma unroll
;     for (int k = 0; k < 3; ++k) { w[k][0] = *(const f32x4*)(cw + k * 512 + c0); w[k][1] = *(const f32x4*)(cw + k * 512 + c0 + 4); }
;     for (int r = gw; r < MP; r += NGW) {
;         v4u* dst = (v4u*)(AO + (size_t)r * 1024 + 512 + c0);
;         if (r >= M_REAL) { *dst = (v4u){0u, 0u, 0u, 0u}; *(v4u*)(AO + (size_t)r * 1024 + c0) = (v4u){0u, 0u, 0u, 0u}; continue; }
;         int pos, L;
;         if (r < ROWS_P) { pos = r % L_P; L = L_P; } else { pos = (r - ROWS_P) % L_S; L = L_S; }
; template <int LYR>
; __device__ __forceinline__ void layer_phases(const Args& a, const XcdBarrier& bar, unsigned char* lds, int lo, int hi) {
;     ...
;     if (PH_IN(P0 + 2)) {
;         { LAUNDER_BASES(); conv_pass(P_GB, P_U, a.in[9] + (size_t)LYR * 3 * 512, P_AO, gw, NGW, lane); }
;         __syncthreads();
.LBB0_506:
	v_mov_b32_e32 v255, 2
	s_cmp_lt_i32 s94, 4
	s_cselect_b64 s[2:3], -1, 0
	v_writelane_b32 v250, s2, 20
	s_and_b64 s[0:1], s[2:3], s[0:1]
	s_andn2_b64 vcc, exec, s[0:1]
	v_writelane_b32 v250, s3, 21
	v_writelane_b32 v250, s96, 22
	s_nop 1
	v_writelane_b32 v250, s97, 23
	v_writelane_b32 v250, s71, 24
	v_writelane_b32 v250, s88, 25
	s_nop 1
	v_writelane_b32 v250, s89, 26
	v_writelane_b32 v250, s90, 27
	v_writelane_b32 v250, s91, 28
	v_writelane_b32 v250, s92, 29
	v_writelane_b32 v250, s93, 30
	v_writelane_b32 v250, s94, 31
	v_writelane_b32 v250, s95, 32
	s_cbranch_vccnz .LBB0_612
	s_cmp_lt_u32 s70, 120
	s_cbranch_scc1 .Lattn_go_l0
	v_mov_b32_e32 v255, 1
	s_branch .Lattn_go_l0
.Lconv_do_l0:
	s_mov_b64 s[2:3], s[92:93]
	s_mov_b64 s[0:1], s[90:91]
	v_mov_b32_e32 v0, v182
	v_readfirstlane_b32 s0, v183
	s_lshr_b32 s1, s0, 6
	s_mov_b32 s4, s70
	s_mov_b32 s0, s96
	s_lshl_b32 s4, s4, 3
	s_sub_i32 s4, s4, 960
	s_mov_b32 s0, 136
	s_add_i32 s1, s4, s1
	s_cmp_gt_i32 s1, 0x101ff
	s_cbranch_scc1 .LBB0_522
	v_lshlrev_b32_e32 v24, 3, v0
	v_readlane_b32 s4, v250, 2
	s_waitcnt lgkmcnt(0)
	v_ashrrev_i32_e32 v25, 31, v24
	v_readlane_b32 s6, v250, 4
	v_readlane_b32 s7, v250, 5
	v_readlane_b32 s5, v250, 3
	s_mov_b64 s[4:5], 0x1000
	v_lshl_add_u64 v[20:21], v[24:25], 2, s[6:7]
	v_add_co_u32_e32 v16, vcc, 0x1000, v20
	global_load_dwordx4 v[0:3], v[20:21], off offset:2048
	global_load_dwordx4 v[4:7], v[20:21], off
	global_load_dwordx4 v[8:11], v[20:21], off offset:2064
	global_load_dwordx4 v[12:15], v[20:21], off offset:16
	v_addc_co_u32_e32 v17, vcc, 0, v21, vcc
	v_lshl_add_u64 v[20:21], v[20:21], 0, s[4:5]
	global_load_dwordx4 v[16:19], v[16:17], off
	v_readlane_b32 s10, v250, 8
	global_load_dwordx4 v[20:23], v[20:21], off offset:16
	v_readlane_b32 s11, v250, 9
	v_readlane_b32 s12, v250, 10
	v_readlane_b32 s13, v250, 11
	v_readlane_b32 s8, v250, 6
	v_readlane_b32 s9, v250, 7
	s_mov_b64 s[4:5], 0xc100000
	s_mov_b64 s[10:11], 0x10180000
	s_mov_b64 s[12:13], 0x14200000
	v_lshl_add_u64 v[24:25], v[24:25], 1, s[2:3]
	s_lshl_b32 s6, s0, 3
	s_mov_b32 s0, 0
	s_add_i32 s7, s1, 0xffff3ef0
	s_mov_b32 s8, 0xffff0000
	s_movk_i32 s9, 0x7fff
	v_lshl_add_u64 v[38:39], v[24:25], 0, s[4:5]
	v_lshl_add_u64 v[40:41], v[24:25], 0, s[10:11]
	v_lshl_add_u64 v[42:43], v[24:25], 0, s[12:13]
	v_mov_b32_e32 v48, 0x4010
	v_readlane_b32 s14, v250, 12
	v_readlane_b32 s15, v250, 13
	v_readlane_b32 s16, v250, 14
	v_readlane_b32 s17, v250, 15
	v_readlane_b32 s18, v250, 16
	v_readlane_b32 s19, v250, 17
	s_waitcnt vmcnt(5)
	v_mov_b32_e32 v44, v1
	v_mov_b32_e32 v45, v3
	s_waitcnt vmcnt(4)
	v_mov_b32_e32 v46, v5
	v_mov_b32_e32 v47, v7
	v_mov_b32_e32 v1, v2
	v_mov_b32_e32 v5, v6
	s_waitcnt vmcnt(3)
	v_mov_b32_e32 v2, v9
	v_mov_b32_e32 v3, v11
	s_waitcnt vmcnt(2)
	v_mov_b32_e32 v6, v13
	v_mov_b32_e32 v7, v15
	v_mov_b32_e32 v9, v10
	v_mov_b32_e32 v13, v14
	s_waitcnt vmcnt(1)
	v_mov_b32_e32 v10, v17
	v_mov_b32_e32 v11, v19
	v_mov_b32_e32 v17, v18
	s_waitcnt vmcnt(0)
	v_mov_b32_e32 v14, v21
	v_mov_b32_e32 v15, v23
	v_mov_b32_e32 v21, v22
	s_branch .LBB0_510

; __device__ __forceinline__ void conv_pass(const bf16* GB, const bf16* U, const float* cw  , bf16* AO, int gw, int NGW, int lane) {
;     ...
;         if (r >= M_REAL) { *dst = (v4u){0u, 0u, 0u, 0u}; *(v4u*)(AO + (size_t)r * 1024 + c0) = (v4u){0u, 0u, 0u, 0u}; continue; }
; __device__ __forceinline__ int attn_next(int i, int G, int bx) {
;     if (G == 256) {
;         const int vcu = (bx & 7) * 32 + (bx >> 3), x = vcu >> 5, c = vcu & 31;
;         if (i == 0) return 64 * x + c;
;         if (i == 1) return 64 * x + 32 + c;
;         if (i < 4) { const int f = c + 32 * (i - 2); return NU_S + NU_PC + 72 * x + (f >> 3) * 9 + (f & 7); }
;         if (i == 4 && c < 15) return (c < 8) ? NU_S + NU_PC + 72 * x + c * 9 + 8 : NU_S + 7 * x + (c - 8);
;         return -1;
.LBB0_521:
	s_mov_b32 s2, s0
	s_mov_b32 s3, s0
	s_mov_b32 s1, s0
	v_mov_b64_e32 v[24:25], s[2:3]
	v_mov_b64_e32 v[22:23], s[0:1]
	global_store_dwordx4 v[18:19], v[22:25], off offset:1024
	global_store_dwordx4 v[18:19], v[22:25], off
	s_branch .LBB0_509
.LBB0_522:
	s_branch .LBB0_612
.Lattn_go_l0:
	v_readfirstlane_b32 s0, v183
	s_mov_b64 s[6:7], s[92:93]
	s_mov_b64 s[16:17], s[90:91]
	s_lshr_b32 s0, s0, 6
	v_mov_b32_e32 v0, v182
	s_mov_b32 s1, s96
	s_waitcnt lgkmcnt(0)
	s_barrier
	s_cmpk_lg_i32 s1, 0x100
	v_writelane_b32 v250, s1, 33
	s_cselect_b64 s[0:1], -1, 0
	v_writelane_b32 v250, s0, 34
	s_mov_b32 s71, 0
	v_mov_b32_e32 v1, 0
	v_writelane_b32 v250, s1, 35
	s_lshl_b32 s0, s70, 5
	s_and_b32 s0, s0, 0xe0
	s_ashr_i32 s1, s70, 3
	s_add_i32 s0, s0, s1
	s_ashr_i32 s0, s0, 5
	s_and_b32 s2, s1, 31
	s_lshl_b32 s3, s0, 6
	v_writelane_b32 v250, s70, 36
	s_or_b32 s3, s3, s2
	v_writelane_b32 v250, s3, 37
	s_or_b32 s3, s3, 32
	s_cmp_lt_u32 s2, 15
	v_writelane_b32 v250, s3, 38
	s_cselect_b64 s[4:5], -1, 0
	v_writelane_b32 v250, s4, 39
	s_mul_i32 s3, s0, 7
	s_mulk_i32 s0, 0x48
	v_writelane_b32 v250, s5, 40
	s_mul_i32 s4, s2, 9
	s_and_b32 s1, s1, 7
	s_add_i32 s3, s2, s3
	s_add_i32 s4, s4, s0
	s_or_b32 s5, s2, 0xffffffc0
	s_or_b32 s0, s0, s1
	s_addk_i32 s3, 0x1f8
	s_addk_i32 s4, 0x240
	v_writelane_b32 v250, s5, 41
	s_addk_i32 s0, 0x238
	v_writelane_b32 v250, s0, 42
	s_add_u32 s0, s6, 0x10000
	v_writelane_b32 v250, s0, 43
	s_addc_u32 s0, s7, 0
	v_writelane_b32 v250, s0, 44
	s_add_u32 s0, s16, 0x60c0000
	v_writelane_b32 v250, s0, 45
	s_addc_u32 s0, s17, 0
	v_writelane_b32 v250, s0, 46
	s_add_u32 s0, s16, 0xe1c0000
	v_writelane_b32 v250, s0, 47
	s_addc_u32 s0, s17, 0
	v_writelane_b32 v250, s0, 48
	s_add_u32 s0, s16, 0xa140000
	v_writelane_b32 v250, s0, 49
	s_addc_u32 s0, s17, 0
	v_writelane_b32 v250, s0, 50
	s_add_u32 s0, s6, 0x14200000
	v_writelane_b32 v250, s6, 51
	s_addc_u32 s1, s7, 0
	s_cmp_lt_u32 s2, 8
	v_writelane_b32 v250, s7, 52
	v_writelane_b32 v250, s0, 53
	s_mov_b32 s81, 0x8000
	s_mov_b32 s89, 0x4138aa3b
	v_writelane_b32 v250, s1, 54
	s_cselect_b32 s0, s4, s3
	v_writelane_b32 v250, s0, 55
	s_movk_i32 s88, 0x7fff
	v_mov_b32_e32 v194, 0xf149f2ca
	v_mov_b32_e32 v195, 1
	s_mov_b32 s80, 0
	v_writelane_b32 v250, s16, 56
	s_nop 1
	v_writelane_b32 v250, s17, 57
	s_branch .LBB0_525

; #define PH_SYNC(p) do { if (lo <= (p) && (p) + 1 < hi) xcd_barrier(bar); } while (0)
; __device__ __forceinline__ void xcd_barrier(const XcdBarrier& b) {
;     asm volatile("s_waitcnt vmcnt(0)" ::: "memory");
;     __syncthreads();
;     if (threadIdx.x == 0) {
;         unsigned* bar = b.bar;
;         __builtin_amdgcn_s_waitcnt(0);
;         unsigned nloc = b.st[0], nx = b.st[1];
;         if (nloc == 0u) { xcd_barrier_complete(bar, b.x, nloc, nx); b.st[0] = nloc; b.st[1] = nx; }
; template <int LYR>
; __device__ __forceinline__ void layer_phases(const Args& a, const XcdBarrier& bar, unsigned char* lds, int lo, int hi) {
;     ...
;     PH_SYNC(P0 + 2);
.LBB0_612:
	v_readfirstlane_b32 vcc_lo, v255
	v_mov_b32_e32 v255, 2
	s_cmp_eq_u32 vcc_lo, 1
	s_cbranch_scc1 .Lconv_do_l0
	s_cmp_gt_i32 s95, 4
	v_readlane_b32 s2, v250, 20
	s_cselect_b64 s[0:1], -1, 0
	v_readlane_b32 s3, v250, 21
	s_and_b64 s[2:3], s[2:3], s[0:1]
	s_andn2_b64 vcc, exec, s[2:3]
	s_cbranch_vccnz .LBB0_657
	s_waitcnt vmcnt(0)
	s_waitcnt lgkmcnt(0)
	s_barrier
	s_mov_b64 s[2:3], exec
	v_readlane_b32 s4, v250, 0
	v_readlane_b32 s5, v250, 1
	s_and_b64 s[4:5], s[2:3], s[4:5]
	s_mov_b64 exec, s[4:5]
	s_cbranch_execz .LBB0_656
	s_add_i32 s4, 0, 0x23fc0
	v_mov_b32_e32 v0, s4
	s_waitcnt vmcnt(0) expcnt(0) lgkmcnt(0)
	ds_read_b32 v2, v0
	s_add_i32 s4, 0, 0x23fc4
	v_mov_b32_e32 v0, s4
	ds_read_b32 v0, v0
	s_waitcnt lgkmcnt(1)
	v_cmp_ne_u32_e32 vcc, 0, v2
	s_cbranch_vccnz .LBB0_627
	s_add_u32 s4, s72, 0x1000
	s_addc_u32 s5, s73, 0
	s_add_u32 s6, s72, 0x1100
	s_addc_u32 s7, s73, 0
	s_add_u32 s8, s72, 0x1200
	s_addc_u32 s9, s73, 0
	s_mul_i32 s18, s97, s71
	s_add_u32 s10, s72, 0x1300
	s_mul_i32 s18, s18, s96
	s_addc_u32 s11, s73, 0
	s_mov_b32 s19, 1
	v_mov_b32_e32 v16, 0
	s_branch .LBB0_617
